# MLA loop: softmax shift folded into QK^T accumulation via f32 MFMA init (v_mfma_f32_32x32x2_f32), 64 v_sub per iteration removed
# speedup vs baseline: 1.0110x; 1.0092x over previous
.LBB0_744:
	s_and_b64 vcc, exec, s[0:1]
	s_cbranch_vccz .LBB0_739
	s_lshl_b32 s0, s5, 8
	v_mov_b32_e32 v29, v193
	s_and_b32 s0, s0, 0x700
	s_ashr_i32 s3, s5, 6
	v_and_b32_e32 v0, 0xffffffc0, v29
	v_and_b32_e32 v30, 31, v29
	v_add_u32_e32 v0, s0, v0
	s_bfe_u32 s8, s5, 0x30003
	s_lshl_b32 s1, s3, 3
	v_or_b32_e32 v188, v0, v30
	s_or_b32 s13, s1, s8
	v_ashrrev_i32_e32 v189, 31, v188
	v_mad_i64_i32 v[2:3], s[0:1], s13, v198, v[188:189]
	v_mov_b64_e32 v[4:5], s[40:41]
	s_movk_i32 s6, 0xc0
	v_bfe_u32 v31, v29, 5, 1
	v_mad_u64_u32 v[4:5], s[0:1], v2, s6, v[4:5]
	v_lshlrev_b32_e32 v0, 4, v31
	v_mad_i32_i24 v5, v3, s6, v5
	v_lshl_add_u64 v[26:27], v[4:5], 0, v[0:1]
	s_mov_b64 s[0:1], 0x1800
	v_lshl_add_u64 v[22:23], v[26:27], 0, s[0:1]
	s_movk_i32 s0, 0x1000
	v_add_co_u32_e32 v2, vcc, s0, v26
	s_nop 1
	v_addc_co_u32_e32 v3, vcc, 0, v27, vcc
	s_barrier
	global_load_dwordx4 v[2:5], v[2:3], off offset:2048
	s_nop 0
	global_load_dwordx4 v[6:9], v[22:23], off offset:32
	global_load_dwordx4 v[10:13], v[22:23], off offset:64
	global_load_dwordx4 v[14:17], v[22:23], off offset:96
	global_load_dwordx4 v[18:21], v[22:23], off offset:128
	s_nop 0
	global_load_dwordx4 v[22:25], v[22:23], off offset:160
	v_lshrrev_b32_e32 v29, 1, v29
	s_mov_b32 s0, 0xfffffe0
	v_and_or_b32 v29, v29, s0, v30
	s_mul_i32 s9, s13, 0x6c000
	v_add_u32_e32 v192, 0, v0
	v_readlane_b32 s0, v254, 7
	s_movk_i32 s16, 0xd0
	s_add_u32 s6, s0, s9
	v_mad_u64_u32 v[194:195], s[0:1], v29, s16, v[192:193]
	s_mul_hi_i32 s10, s13, 0x6c000
	v_readlane_b32 s0, v254, 8
	v_mov_b32_e32 v28, v193
	s_mul_hi_i32 s12, s13, 0x48000
	s_mul_i32 s13, s13, 0x48000
	s_addc_u32 s7, s0, s10
	v_readlane_b32 s0, v254, 9
	s_add_u32 s0, s0, s13
	v_readlane_b32 s1, v254, 10
	global_load_dwordx4 v[144:147], v[26:27], off
	global_load_dwordx4 v[148:151], v[26:27], off offset:32
	global_load_dwordx4 v[152:155], v[26:27], off offset:64
	global_load_dwordx4 v[156:159], v[26:27], off offset:96
	global_load_dwordx4 v[160:163], v[26:27], off offset:128
	global_load_dwordx4 v[164:167], v[26:27], off offset:160
	s_addc_u32 s1, s1, s12
	s_movk_i32 s17, 0x2000
	s_movk_i32 s11, 0x1200
	v_lshlrev_b32_e32 v190, 3, v31
	v_mul_u32_u24_e32 v191, 0xd0, v30
	v_mov_b32_e32 v215, 0
	v_mov_b32_e32 v195, 0
	s_waitcnt vmcnt(11)
	ds_write_b128 v194, v[2:5] offset:47104
	s_waitcnt vmcnt(10)
	ds_write_b128 v194, v[6:9] offset:47136
	s_waitcnt vmcnt(9)
	ds_write_b128 v194, v[10:13] offset:47168
	s_waitcnt vmcnt(8)
	ds_write_b128 v194, v[14:17] offset:47200
	s_waitcnt vmcnt(7)
	ds_write_b128 v194, v[18:21] offset:47232
	s_waitcnt vmcnt(6)
	ds_write_b128 v194, v[22:25] offset:47264
	v_mov_b32_e32 v23, v193
	v_ashrrev_i32_e32 v29, 31, v28
	v_lshlrev_b32_e32 v0, 4, v28
	v_add_u32_e32 v2, 0x100, v28
	v_lshl_add_u64 v[4:5], v[28:29], 4, s[6:7]
	v_and_b32_e32 v0, 0x70, v0
	v_ashrrev_i32_e32 v14, 3, v28
	v_ashrrev_i32_e32 v3, 31, v2
	v_ashrrev_i32_e32 v16, 3, v2
	v_add_co_u32_e32 v10, vcc, s17, v4
	v_lshl_add_u64 v[12:13], s[0:1], 0, v[0:1]
	v_lshl_add_u64 v[6:7], v[2:3], 4, s[6:7]
	v_addc_co_u32_e32 v11, vcc, 0, v5, vcc
	v_mad_i64_i32 v[14:15], s[14:15], v14, s11, v[12:13]
	v_mad_i64_i32 v[18:19], s[14:15], v16, s11, v[12:13]
	global_load_dwordx4 v[2:5], v[4:5], off
	s_nop 0
	global_load_dwordx4 v[6:9], v[6:7], off
	s_nop 0
	global_load_dwordx4 v[10:13], v[10:11], off
	s_nop 0
	global_load_dwordx4 v[14:17], v[14:15], off
	s_nop 0
	global_load_dwordx4 v[18:21], v[18:19], off
	s_mov_b32 s14, 0x2aaaaaab
	v_mov_b32_e32 v22, v193
	v_mul_hi_i32 v0, v23, s14
	v_add_u32_e32 v28, 0x100, v23
	v_add_u32_e32 v29, 0x200, v23
	v_lshlrev_b32_e32 v24, 4, v23
	v_lshrrev_b32_e32 v26, 31, v0
	v_ashrrev_i32_e32 v0, 1, v0
	v_mul_hi_i32 v27, v28, s14
	v_mul_hi_i32 v32, v29, s14
	v_and_b32_e32 v24, 0x70, v24
	v_add_u32_e32 v26, v0, v26
	v_lshrrev_b32_e32 v34, 31, v27
	v_ashrrev_i32_e32 v27, 1, v27
	v_lshrrev_b32_e32 v25, 3, v23
	v_lshrrev_b32_e32 v33, 3, v28
	v_lshrrev_b32_e32 v35, 31, v32
	v_ashrrev_i32_e32 v32, 1, v32
	v_add_u32_e32 v0, 0, v24
	v_mul_lo_u32 v36, v26, 12
	v_add_u32_e32 v34, v27, v34
	v_mul_lo_u32 v37, v26, s16
	v_add_u32_e32 v32, v32, v35
	v_mad_u64_u32 v[24:25], s[14:15], v25, s91, v[0:1]
	v_mad_u64_u32 v[26:27], s[14:15], v33, s91, v[0:1]
	v_sub_u32_e32 v0, v23, v36
	v_mul_lo_u32 v23, v34, 12
	v_mul_lo_u32 v27, v32, 12
	v_sub_u32_e32 v23, v28, v23
	v_mul_lo_u32 v25, v34, s16
	v_lshlrev_b32_e32 v0, 4, v0
	v_sub_u32_e32 v27, v29, v27
	v_lshlrev_b32_e32 v23, 4, v23
	s_add_u32 s6, s6, 0x3000
	v_mul_lo_u32 v32, v32, s16
	v_add3_u32 v0, 0, v37, v0
	v_lshlrev_b32_e32 v27, 4, v27
	v_add3_u32 v23, 0, v25, v23
	s_addc_u32 s7, s7, 0
	v_add3_u32 v25, 0, v32, v27
	s_waitcnt vmcnt(4)
	ds_write_b128 v0, v[2:5]
	s_waitcnt vmcnt(3)
	ds_write_b128 v23, v[6:9]
	s_waitcnt vmcnt(2)
	ds_write_b128 v25, v[10:13]
	s_waitcnt vmcnt(1)
	ds_write_b128 v24, v[14:17] offset:13312
	s_waitcnt vmcnt(0)
	ds_write_b128 v26, v[18:21] offset:13312
	v_mov_b32_e32 v204, v0
	v_mov_b32_e32 v205, v23
	v_mov_b32_e32 v209, v25
	v_mov_b32_e32 v212, v24
	v_and_b32_e32 v235, 32, v193
	v_sub_u32_e32 v235, 32, v235
	v_cvt_f32_u32_e32 v235, v235
	v_mul_f32_e32 v235, 0xbd000000, v235
	v_mov_b32_e32 v14, v1
	v_ashrrev_i32_e32 v23, 31, v22
	v_add_u32_e32 v2, 0x100, v22
	v_lshlrev_b32_e32 v0, 4, v22
	v_lshl_add_u64 v[4:5], v[22:23], 4, s[6:7]
	v_ashrrev_i32_e32 v3, 31, v2
	v_and_b32_e32 v0, 0x70, v0
	v_add_co_u32_e32 v6, vcc, s17, v4
	v_ashrrev_i32_e32 v10, 3, v22
	v_ashrrev_i32_e32 v11, 3, v2
	v_lshl_add_u64 v[2:3], v[2:3], 4, s[6:7]
	v_addc_co_u32_e32 v7, vcc, 0, v5, vcc
	v_lshl_add_u64 v[8:9], s[0:1], 0, v[0:1]
	global_load_dwordx4 v[168:171], v[4:5], off
	global_load_dwordx4 v[172:175], v[2:3], off
	v_mad_i64_i32 v[2:3], s[0:1], v10, s11, v[8:9]
	v_mad_i64_i32 v[4:5], s[0:1], v11, s11, v[8:9]
	global_load_dwordx4 v[176:179], v[6:7], off
	global_load_dwordx4 v[180:183], v[2:3], off offset:128
	global_load_dwordx4 v[184:187], v[4:5], off offset:128
	v_and_b32_e32 v2, 64, v200
	v_xor_b32_e32 v0, 32, v200
	v_add_u32_e32 v2, 64, v2
	v_cmp_lt_i32_e32 vcc, v0, v2
	v_readlane_b32 s0, v255, 23
	s_add_u32 s9, s0, s9
	v_cndmask_b32_e32 v0, v200, v0, vcc
	v_readlane_b32 s0, v255, 24
	v_lshlrev_b32_e32 v189, 2, v0
	v_sub_u32_e32 v0, v192, v190
	v_mul_u32_u24_e32 v2, 0x48, v30
	s_addc_u32 s10, s0, s10
	v_readlane_b32 s0, v255, 25
	v_mov_b32_e32 v15, v1
	v_lshl_add_u32 v214, v2, 1, v0
	s_add_u32 s0, s0, s13
	v_readlane_b32 s1, v255, 26
	v_mov_b32_e32 v0, v1
	v_mov_b32_e32 v2, v1
	v_mov_b32_e32 v3, v1
	v_mov_b32_e32 v4, v1
	v_mov_b32_e32 v5, v1
	v_mov_b32_e32 v6, v1
	v_mov_b32_e32 v7, v1
	v_mov_b32_e32 v8, v1
	v_mov_b32_e32 v9, v1
	v_mov_b32_e32 v10, v1
	v_mov_b32_e32 v11, v1
	v_mov_b32_e32 v12, v1
	v_mov_b32_e32 v13, v1
	v_mov_b64_e32 v[30:31], v[14:15]
	v_mov_b64_e32 v[46:47], v[14:15]
	v_mov_b64_e32 v[62:63], v[14:15]
	v_mov_b64_e32 v[78:79], v[14:15]
	s_movk_i32 s16, 0x2000
	s_mov_b32 s11, 0
	s_addc_u32 s1, s1, s12
	s_mov_b64 s[6:7], 0
	v_mov_b64_e32 v[28:29], v[12:13]
	v_mov_b64_e32 v[26:27], v[10:11]
	v_mov_b64_e32 v[24:25], v[8:9]
	v_mov_b64_e32 v[22:23], v[6:7]
	v_mov_b64_e32 v[20:21], v[4:5]
	v_mov_b64_e32 v[18:19], v[2:3]
	v_mov_b64_e32 v[16:17], v[0:1]
	v_mov_b64_e32 v[44:45], v[12:13]
	v_mov_b64_e32 v[42:43], v[10:11]
	v_mov_b64_e32 v[40:41], v[8:9]
	v_mov_b64_e32 v[38:39], v[6:7]
	v_mov_b64_e32 v[36:37], v[4:5]
	v_mov_b64_e32 v[34:35], v[2:3]
	v_mov_b64_e32 v[32:33], v[0:1]
	v_mov_b64_e32 v[60:61], v[12:13]
	v_mov_b64_e32 v[58:59], v[10:11]
	v_mov_b64_e32 v[56:57], v[8:9]
	v_mov_b64_e32 v[54:55], v[6:7]
	v_mov_b64_e32 v[52:53], v[4:5]
	v_mov_b64_e32 v[50:51], v[2:3]
	v_mov_b64_e32 v[48:49], v[0:1]
	v_mov_b64_e32 v[76:77], v[12:13]
	v_mov_b64_e32 v[74:75], v[10:11]
	v_mov_b64_e32 v[72:73], v[8:9]
	v_mov_b64_e32 v[70:71], v[6:7]
	v_mov_b64_e32 v[68:69], v[4:5]
	v_mov_b64_e32 v[66:67], v[2:3]
	v_mov_b64_e32 v[64:65], v[0:1]
	v_mov_b32_e32 v0, 0
	v_mov_b32_e32 v14, 0
	s_waitcnt lgkmcnt(0)
	s_barrier
.LBB0_746:
	s_bitcmp1_b32 s11, 0
	s_cselect_b32 s12, 0x2c00, 0
	s_lshl_b32 s13, s12, 1
	v_add3_u32 v15, v192, s13, v191
	ds_read_b128 v[2:5], v15
	ds_read_b128 v[10:13], v194 offset:47104
	ds_read_b128 v[240:243], v15 offset:32
	ds_read_b128 v[216:219], v194 offset:47136
	ds_read_b128 v[244:247], v15 offset:64
	ds_read_b128 v[6:9], v194 offset:47168
	ds_read_b128 v[248:251], v15 offset:96
	ds_read_b128 v[220:223], v194 offset:47200
	v_mfma_f32_32x32x2_f32 v[112:127], v235, v215, 0
	v_mfma_f32_32x32x2_f32 v[96:111], v235, v14, 0
	v_mfma_f32_32x32x2_f32 v[128:143], v235, v215, 0
	v_mfma_f32_32x32x2_f32 v[80:95], v235, v14, 0
	s_waitcnt lgkmcnt(7)
	v_mfma_f32_32x32x16_bf16 v[112:127], v[2:5], v[144:147], v[112:127]
	s_waitcnt lgkmcnt(6)
	v_mfma_f32_32x32x16_bf16 v[96:111], v[2:5], v[10:13], v[96:111]
	ds_read_b128 v[2:5], v15 offset:128
	ds_read_b128 v[224:227], v194 offset:47232
	s_waitcnt lgkmcnt(7)
	v_mfma_f32_32x32x16_bf16 v[112:127], v[240:243], v[148:151], v[112:127]
	s_waitcnt lgkmcnt(6)
	v_mfma_f32_32x32x16_bf16 v[96:111], v[240:243], v[216:219], v[96:111]
	ds_read_b128 v[240:243], v15 offset:160
	ds_read_b128 v[228:231], v194 offset:47264
	s_waitcnt lgkmcnt(7)
	v_mfma_f32_32x32x16_bf16 v[112:127], v[244:247], v[152:155], v[112:127]
	s_waitcnt lgkmcnt(6)
	v_mfma_f32_32x32x16_bf16 v[96:111], v[244:247], v[6:9], v[96:111]
	ds_read_b128 v[244:247], v15 offset:6656
	s_waitcnt lgkmcnt(6)
	v_mfma_f32_32x32x16_bf16 v[112:127], v[248:251], v[156:159], v[112:127]
	s_waitcnt lgkmcnt(5)
	v_mfma_f32_32x32x16_bf16 v[96:111], v[248:251], v[220:223], v[96:111]
	ds_read_b128 v[248:251], v15 offset:6688
	s_waitcnt lgkmcnt(5)
	v_mfma_f32_32x32x16_bf16 v[112:127], v[2:5], v[160:163], v[112:127]
	s_waitcnt lgkmcnt(4)
	v_mfma_f32_32x32x16_bf16 v[96:111], v[2:5], v[224:227], v[96:111]
	ds_read_b128 v[2:5], v15 offset:6720
	s_waitcnt lgkmcnt(4)
	v_mfma_f32_32x32x16_bf16 v[112:127], v[240:243], v[164:167], v[112:127]
	s_waitcnt lgkmcnt(3)
	v_mfma_f32_32x32x16_bf16 v[96:111], v[240:243], v[228:231], v[96:111]
	ds_read_b128 v[240:243], v15 offset:6752
	s_waitcnt lgkmcnt(3)
	v_mfma_f32_32x32x16_bf16 v[128:143], v[244:247], v[144:147], v[128:143]
	v_mfma_f32_32x32x16_bf16 v[80:95], v[244:247], v[10:13], v[80:95]
	ds_read_b128 v[244:247], v15 offset:6784
	s_waitcnt lgkmcnt(3)
	v_mfma_f32_32x32x16_bf16 v[128:143], v[248:251], v[148:151], v[128:143]
	v_mfma_f32_32x32x16_bf16 v[80:95], v[248:251], v[216:219], v[80:95]
	ds_read_b128 v[248:251], v15 offset:6816
	s_waitcnt lgkmcnt(3)
	v_mfma_f32_32x32x16_bf16 v[128:143], v[2:5], v[152:155], v[128:143]
	v_mfma_f32_32x32x16_bf16 v[80:95], v[2:5], v[6:9], v[80:95]
	s_waitcnt lgkmcnt(2)
	v_mfma_f32_32x32x16_bf16 v[128:143], v[240:243], v[156:159], v[128:143]
	v_mfma_f32_32x32x16_bf16 v[80:95], v[240:243], v[220:223], v[80:95]
	s_waitcnt lgkmcnt(1)
	v_mfma_f32_32x32x16_bf16 v[128:143], v[244:247], v[160:163], v[128:143]
	v_mfma_f32_32x32x16_bf16 v[80:95], v[244:247], v[224:227], v[80:95]
	s_waitcnt lgkmcnt(0)
	v_mfma_f32_32x32x16_bf16 v[128:143], v[248:251], v[164:167], v[128:143]
	v_mfma_f32_32x32x16_bf16 v[80:95], v[248:251], v[228:231], v[80:95]
	v_max_f32_e32 v2, v113, v113
	v_max_f32_e32 v3, v112, v112
	v_max_f32_e32 v2, v3, v2
	v_max3_f32 v2, v2, v114, v115
	v_max3_f32 v2, v2, v116, v117
	v_max3_f32 v2, v2, v118, v119
	v_max3_f32 v2, v2, v120, v121
	v_max3_f32 v2, v2, v122, v123
	v_max3_f32 v2, v2, v124, v125
	v_max3_f32 v2, v2, v126, v127
	s_nop 0
	v_max3_f32 v2, v2, v128, v129
	v_max3_f32 v2, v2, v130, v131
	v_max3_f32 v2, v2, v132, v133
	v_max3_f32 v2, v2, v134, v135
	v_max3_f32 v2, v2, v136, v137
	v_max3_f32 v2, v2, v138, v139
	v_max3_f32 v2, v2, v140, v141
	v_max3_f32 v2, v2, v142, v143
	ds_bpermute_b32 v3, v189, v2
	s_waitcnt lgkmcnt(0)
	v_max_f32_e32 v3, v3, v3
	v_max_f32_e32 v2, v2, v3
	v_cmp_lt_f32_e32 vcc, 0x41000000, v2
	s_cbranch_vccnz .Lmla_rareA
	s_cmp_lg_u32 s11, 0
	s_cbranch_scc1 .LBB0_748
.Lmla_rareA:
	s_cmp_eq_u32 s11, 0
	s_cselect_b32 s13, 0xff800000, 0
	v_max_f32_e32 v3, s13, v2
	v_exp_f32_e64 v2, -v3
	v_add_f32_e32 v215, v215, v3
	v_min_f32_e32 v2, 0x7149f2ca, v2
	v_mul_f32_e32 v0, v0, v2
	v_pk_mul_f32 v[78:79], v[78:79], v[2:3] op_sel_hi:[1,0]
	v_pk_mul_f32 v[76:77], v[76:77], v[2:3] op_sel_hi:[1,0]
	v_pk_mul_f32 v[74:75], v[74:75], v[2:3] op_sel_hi:[1,0]
	v_pk_mul_f32 v[72:73], v[72:73], v[2:3] op_sel_hi:[1,0]
	v_pk_mul_f32 v[70:71], v[70:71], v[2:3] op_sel_hi:[1,0]
	v_pk_mul_f32 v[68:69], v[68:69], v[2:3] op_sel_hi:[1,0]
	v_pk_mul_f32 v[66:67], v[66:67], v[2:3] op_sel_hi:[1,0]
	v_pk_mul_f32 v[64:65], v[64:65], v[2:3] op_sel_hi:[1,0]
	v_pk_mul_f32 v[62:63], v[62:63], v[2:3] op_sel_hi:[1,0]
	v_pk_mul_f32 v[60:61], v[60:61], v[2:3] op_sel_hi:[1,0]
	v_pk_mul_f32 v[58:59], v[58:59], v[2:3] op_sel_hi:[1,0]
	v_pk_mul_f32 v[56:57], v[56:57], v[2:3] op_sel_hi:[1,0]
	v_pk_mul_f32 v[54:55], v[54:55], v[2:3] op_sel_hi:[1,0]
	v_pk_mul_f32 v[52:53], v[52:53], v[2:3] op_sel_hi:[1,0]
	v_pk_mul_f32 v[50:51], v[50:51], v[2:3] op_sel_hi:[1,0]
	v_pk_mul_f32 v[48:49], v[48:49], v[2:3] op_sel_hi:[1,0]
	v_sub_f32_e32 v112, v112, v3
	v_sub_f32_e32 v113, v113, v3
	v_sub_f32_e32 v114, v114, v3
	v_sub_f32_e32 v115, v115, v3
	v_sub_f32_e32 v116, v116, v3
	v_sub_f32_e32 v117, v117, v3
	v_sub_f32_e32 v118, v118, v3
	v_sub_f32_e32 v119, v119, v3
	v_sub_f32_e32 v120, v120, v3
	v_sub_f32_e32 v121, v121, v3
	v_sub_f32_e32 v122, v122, v3
	v_sub_f32_e32 v123, v123, v3
	v_sub_f32_e32 v124, v124, v3
	v_sub_f32_e32 v125, v125, v3
	v_sub_f32_e32 v126, v126, v3
	v_sub_f32_e32 v127, v127, v3
	v_sub_f32_e32 v128, v128, v3
	v_sub_f32_e32 v129, v129, v3
	v_sub_f32_e32 v130, v130, v3
	v_sub_f32_e32 v131, v131, v3
	v_sub_f32_e32 v132, v132, v3
	v_sub_f32_e32 v133, v133, v3
	v_sub_f32_e32 v134, v134, v3
	v_sub_f32_e32 v135, v135, v3
	v_sub_f32_e32 v136, v136, v3
	v_sub_f32_e32 v137, v137, v3
	v_sub_f32_e32 v138, v138, v3
	v_sub_f32_e32 v139, v139, v3
	v_sub_f32_e32 v140, v140, v3
	v_sub_f32_e32 v141, v141, v3
	v_sub_f32_e32 v142, v142, v3
	v_sub_f32_e32 v143, v143, v3
.LBB0_748:
	v_exp_f32_e32 v15, v112
	v_exp_f32_e32 v216, v113
	v_exp_f32_e32 v217, v114
	v_exp_f32_e32 v218, v115
	v_exp_f32_e32 v219, v116
	v_exp_f32_e32 v220, v117
	v_exp_f32_e32 v221, v118
	v_exp_f32_e32 v222, v119
	v_exp_f32_e32 v223, v120
	v_exp_f32_e32 v224, v121
	v_exp_f32_e32 v225, v122
	v_exp_f32_e32 v226, v123
	v_exp_f32_e32 v227, v124
	v_exp_f32_e32 v228, v125
	v_exp_f32_e32 v229, v126
	v_exp_f32_e32 v230, v127
	v_exp_f32_e32 v231, v128
	v_exp_f32_e32 v232, v129
	v_exp_f32_e32 v233, v130
	v_exp_f32_e32 v234, v131
	v_exp_f32_e32 v132, v132
	v_exp_f32_e32 v133, v133
	v_exp_f32_e32 v134, v134
	v_exp_f32_e32 v135, v135
	v_exp_f32_e32 v136, v136
	v_exp_f32_e32 v137, v137
	v_exp_f32_e32 v138, v138
	v_exp_f32_e32 v139, v139
	v_exp_f32_e32 v140, v140
	v_exp_f32_e32 v141, v141
	v_exp_f32_e32 v142, v142
	v_exp_f32_e32 v143, v143
	v_lshl_add_u32 v10, s12, 1, v214
	v_add_u32_e32 v128, 0x3000, v10
	v_add_u32_e32 v129, 0x4000, v10
	ds_read2_b64 v[6:9], v128 offset0:128 offset1:130
	ds_read2_b64 v[2:5], v128 offset0:132 offset1:134
	ds_read2_b64 v[10:13], v129 offset0:192 offset1:194
	v_cvt_pk_bf16_f32 v112, v15, v216
	v_cvt_pk_bf16_f32 v113, v217, v218
	v_cvt_pk_bf16_f32 v114, v219, v220
	v_cvt_pk_bf16_f32 v115, v221, v222
	v_cvt_pk_bf16_f32 v116, v223, v224
	v_cvt_pk_bf16_f32 v117, v225, v226
	s_waitcnt lgkmcnt(2)
	v_mfma_f32_32x32x16_bf16 v[64:79], v[6:9], v[112:115], v[64:79]
	v_cvt_pk_bf16_f32 v118, v227, v228
	v_cvt_pk_bf16_f32 v119, v229, v230
	ds_read2_b64 v[120:123], v129 offset0:200 offset1:202
	v_max_f32_e32 v202, v97, v97
	v_max_f32_e32 v203, v96, v96
	v_max_f32_e32 v202, v203, v202
	v_max3_f32 v202, v202, v98, v99
	s_waitcnt lgkmcnt(1)
	v_mfma_f32_32x32x16_bf16 v[48:63], v[10:13], v[112:115], v[48:63]
	ds_read2_b64 v[112:115], v129 offset0:196 offset1:198
	v_max3_f32 v202, v202, v100, v101
	v_max3_f32 v202, v202, v102, v103
	v_max3_f32 v202, v202, v104, v105
	v_max3_f32 v202, v202, v106, v107
	v_cvt_pk_bf16_f32 v124, v231, v232
	v_cvt_pk_bf16_f32 v125, v233, v234
	v_mfma_f32_32x32x16_bf16 v[64:79], v[2:5], v[116:119], v[64:79]
	v_cvt_pk_bf16_f32 v126, v132, v133
	v_cvt_pk_bf16_f32 v127, v134, v135
	v_max3_f32 v202, v202, v108, v109
	v_max3_f32 v202, v202, v110, v111
	v_max3_f32 v202, v202, v80, v81
	v_max3_f32 v202, v202, v82, v83
	v_max3_f32 v202, v202, v84, v85
	s_waitcnt lgkmcnt(0)
	v_mfma_f32_32x32x16_bf16 v[48:63], v[112:115], v[116:119], v[48:63]
	ds_read2_b64 v[116:119], v128 offset0:136 offset1:138
	v_max3_f32 v202, v202, v86, v87
	v_max3_f32 v202, v202, v88, v89
	v_max3_f32 v202, v202, v90, v91
	v_max3_f32 v202, v202, v92, v93
	v_cvt_pk_bf16_f32 v236, v136, v137
	v_cvt_pk_bf16_f32 v237, v138, v139
	s_waitcnt lgkmcnt(0)
	v_mfma_f32_32x32x16_bf16 v[64:79], v[116:119], v[124:127], v[64:79]
	v_cvt_pk_bf16_f32 v238, v140, v141
	v_cvt_pk_bf16_f32 v239, v142, v143
	v_max3_f32 v202, v202, v94, v95
	ds_bpermute_b32 v203, v189, v202
	s_waitcnt lgkmcnt(0)
	v_max_f32_e32 v203, v203, v203
	v_mfma_f32_32x32x16_bf16 v[48:63], v[120:123], v[124:127], v[48:63]
	ds_read2_b64 v[124:127], v128 offset0:140 offset1:142
	ds_read2_b64 v[128:131], v129 offset0:204 offset1:206
	v_max_f32_e32 v208, v202, v203
	v_cmp_lt_f32_e32 vcc, 0x41000000, v208
	s_waitcnt lgkmcnt(1)
	v_mfma_f32_32x32x16_bf16 v[64:79], v[124:127], v[236:239], v[64:79]
	s_waitcnt lgkmcnt(0)
	v_mfma_f32_32x32x16_bf16 v[48:63], v[128:131], v[236:239], v[48:63]
	s_cbranch_vccnz .Lmla_rareB
	s_cmp_lg_u32 s11, 0
	s_cbranch_scc1 .LBB0_750
.Lmla_rareB:
	s_cmp_eq_u32 s11, 0
	s_cselect_b32 s13, 0xff800000, 0
	v_max_f32_e32 v208, s13, v208
	v_exp_f32_e64 v202, -v208
	v_add_f32_e32 v14, v14, v208
	v_min_f32_e32 v202, 0x7149f2ca, v202
	v_mul_f32_e32 v195, v195, v202
	v_pk_mul_f32 v[46:47], v[46:47], v[202:203] op_sel_hi:[1,0]
	v_pk_mul_f32 v[44:45], v[44:45], v[202:203] op_sel_hi:[1,0]
	v_pk_mul_f32 v[42:43], v[42:43], v[202:203] op_sel_hi:[1,0]
	v_pk_mul_f32 v[40:41], v[40:41], v[202:203] op_sel_hi:[1,0]
	v_pk_mul_f32 v[38:39], v[38:39], v[202:203] op_sel_hi:[1,0]
	v_pk_mul_f32 v[36:37], v[36:37], v[202:203] op_sel_hi:[1,0]
	v_pk_mul_f32 v[34:35], v[34:35], v[202:203] op_sel_hi:[1,0]
	v_pk_mul_f32 v[32:33], v[32:33], v[202:203] op_sel_hi:[1,0]
	v_pk_mul_f32 v[30:31], v[30:31], v[202:203] op_sel_hi:[1,0]
	v_pk_mul_f32 v[28:29], v[28:29], v[202:203] op_sel_hi:[1,0]
	v_pk_mul_f32 v[26:27], v[26:27], v[202:203] op_sel_hi:[1,0]
	v_pk_mul_f32 v[24:25], v[24:25], v[202:203] op_sel_hi:[1,0]
	v_pk_mul_f32 v[22:23], v[22:23], v[202:203] op_sel_hi:[1,0]
	v_pk_mul_f32 v[20:21], v[20:21], v[202:203] op_sel_hi:[1,0]
	v_pk_mul_f32 v[18:19], v[18:19], v[202:203] op_sel_hi:[1,0]
	v_pk_mul_f32 v[16:17], v[16:17], v[202:203] op_sel_hi:[1,0]
	v_sub_f32_e32 v96, v96, v208
	v_sub_f32_e32 v97, v97, v208
	v_sub_f32_e32 v98, v98, v208
	v_sub_f32_e32 v99, v99, v208
	v_sub_f32_e32 v100, v100, v208
	v_sub_f32_e32 v101, v101, v208
	v_sub_f32_e32 v102, v102, v208
	v_sub_f32_e32 v103, v103, v208
	v_sub_f32_e32 v104, v104, v208
	v_sub_f32_e32 v105, v105, v208
	v_sub_f32_e32 v106, v106, v208
	v_sub_f32_e32 v107, v107, v208
	v_sub_f32_e32 v108, v108, v208
	v_sub_f32_e32 v109, v109, v208
	v_sub_f32_e32 v110, v110, v208
	v_sub_f32_e32 v111, v111, v208
	v_sub_f32_e32 v80, v80, v208
	v_sub_f32_e32 v81, v81, v208
	v_sub_f32_e32 v82, v82, v208
	v_sub_f32_e32 v83, v83, v208
	v_sub_f32_e32 v84, v84, v208
	v_sub_f32_e32 v85, v85, v208
	v_sub_f32_e32 v86, v86, v208
	v_sub_f32_e32 v87, v87, v208
	v_sub_f32_e32 v88, v88, v208
	v_sub_f32_e32 v89, v89, v208
	v_sub_f32_e32 v90, v90, v208
	v_sub_f32_e32 v91, v91, v208
	v_sub_f32_e32 v92, v92, v208
	v_sub_f32_e32 v93, v93, v208
	v_sub_f32_e32 v94, v94, v208
	v_sub_f32_e32 v95, v95, v208
.LBB0_750:
	v_exp_f32_e32 v96, v96
	v_exp_f32_e32 v97, v97
	v_exp_f32_e32 v98, v98
	v_exp_f32_e32 v99, v99
	v_exp_f32_e32 v100, v100
	v_exp_f32_e32 v101, v101
	v_exp_f32_e32 v102, v102
	v_exp_f32_e32 v103, v103
	v_cvt_pk_bf16_f32 v236, v96, v97
	v_cvt_pk_bf16_f32 v237, v98, v99
	v_cvt_pk_bf16_f32 v238, v100, v101
	v_cvt_pk_bf16_f32 v239, v102, v103
	s_nop 1
	v_mfma_f32_32x32x16_bf16 v[32:47], v[6:9], v[236:239], v[32:47]
	v_exp_f32_e32 v104, v104
	v_mfma_f32_32x32x16_bf16 v[16:31], v[10:13], v[236:239], v[16:31]
	v_exp_f32_e32 v105, v105
	v_exp_f32_e32 v106, v106
	v_exp_f32_e32 v107, v107
	v_exp_f32_e32 v108, v108
	v_exp_f32_e32 v109, v109
	v_exp_f32_e32 v110, v110
	v_exp_f32_e32 v111, v111
	v_exp_f32_e32 v7, v82
	v_exp_f32_e32 v8, v83
	v_exp_f32_e32 v9, v84
	v_exp_f32_e32 v10, v85
	v_cvt_pk_bf16_f32 v82, v104, v105
	v_cvt_pk_bf16_f32 v83, v106, v107
	v_cvt_pk_bf16_f32 v84, v108, v109
	v_cvt_pk_bf16_f32 v85, v110, v111
	v_exp_f32_e32 v6, v81
	s_nop 0
	v_mfma_f32_32x32x16_bf16 v[32:47], v[2:5], v[82:85], v[32:47]
	v_exp_f32_e32 v2, v86
	v_exp_f32_e32 v3, v87
	v_exp_f32_e32 v80, v80
	v_mfma_f32_32x32x16_bf16 v[16:31], v[112:115], v[82:85], v[16:31]
	v_cvt_pk_bf16_f32 v82, v80, v6
	v_cvt_pk_bf16_f32 v83, v7, v8
	v_cvt_pk_bf16_f32 v84, v9, v10
	v_cvt_pk_bf16_f32 v85, v2, v3
	v_exp_f32_e32 v4, v88
	v_exp_f32_e32 v5, v89
	v_mfma_f32_32x32x16_bf16 v[32:47], v[116:119], v[82:85], v[32:47]
	v_exp_f32_e32 v11, v90
	v_exp_f32_e32 v12, v91
	v_exp_f32_e32 v13, v92
	v_exp_f32_e32 v81, v93
	v_exp_f32_e32 v86, v94
	v_mfma_f32_32x32x16_bf16 v[16:31], v[120:123], v[82:85], v[16:31]
	v_exp_f32_e32 v83, v95
	v_mov_b32_e32 v82, v86
	v_cvt_pk_bf16_f32 v84, v4, v5
	v_cvt_pk_bf16_f32 v85, v11, v12
	v_cvt_pk_bf16_f32 v86, v13, v81
	v_cvt_pk_bf16_f32 v87, v82, v83
	s_add_i32 s12, s11, 1
	s_cmp_gt_u32 s11, 34
	v_mfma_f32_32x32x16_bf16 v[32:47], v[124:127], v[84:87], v[32:47]
	s_movk_i32 s14, 0xd0
	v_mfma_f32_32x32x16_bf16 v[16:31], v[128:131], v[84:87], v[16:31]
	s_cbranch_scc1 .LBB0_753
	s_bitcmp1_b32 s12, 0
	s_cselect_b32 s11, 0x5800, 0
	v_add_u32_e32 v84, s11, v204
	v_add_u32_e32 v85, s11, v205
	v_add_u32_e32 v86, s11, v209
	v_add_u32_e32 v87, s11, v212
	s_waitcnt vmcnt(4)
	ds_write_b128 v84, v[168:171]
	s_waitcnt vmcnt(3)
	ds_write_b128 v85, v[172:175]
	s_waitcnt vmcnt(2)
	ds_write_b128 v86, v[176:179]
	s_waitcnt vmcnt(1)
	ds_write_b128 v87, v[180:183] offset:13312
	s_waitcnt vmcnt(0)
	ds_write_b128 v87, v[184:187] offset:17920
	s_cmp_eq_u32 s6, 0x66000
	s_cbranch_scc1 .LBB0_753
	v_mov_b32_e32 v84, v193
	s_add_u32 s14, s9, s6
	s_addc_u32 s15, s10, s7
	v_ashrrev_i32_e32 v85, 31, v84
	v_add_u32_e32 v88, 0x100, v84
	v_lshl_add_u64 v[86:87], v[84:85], 4, s[14:15]
	v_ashrrev_i32_e32 v89, 31, v88
	v_lshl_add_u64 v[90:91], v[88:89], 4, s[14:15]
	global_load_dwordx4 v[168:171], v[86:87], off
	global_load_dwordx4 v[172:175], v[90:91], off
	v_add_co_u32_e32 v86, vcc, s16, v86
	v_ashrrev_i32_e32 v85, 3, v84
	s_nop 0
	v_addc_co_u32_e32 v87, vcc, 0, v87, vcc
	s_movk_i32 s11, 0x1200
	v_lshlrev_b32_e32 v84, 4, v84
	global_load_dwordx4 v[176:179], v[86:87], off
	v_mad_i64_i32 v[86:87], s[14:15], v85, s11, 0
	v_and_b32_e32 v89, 0x70, v84
	v_or_b32_e32 v86, v86, v89
	v_lshl_add_u64 v[84:85], s[0:1], 0, v[86:87]
	v_ashrrev_i32_e32 v86, 3, v88
	v_mad_i64_i32 v[86:87], s[14:15], v86, s11, 0
	v_or_b32_e32 v86, v86, v89
	v_lshl_add_u64 v[86:87], s[0:1], 0, v[86:87]
	global_load_dwordx4 v[180:183], v[84:85], off
	global_load_dwordx4 v[184:187], v[86:87], off
